# scan chunk: removed 2 dead s_mov (old per-step masks) and 1 redundant s_nop before epilogue DPP; 3 fewer issue slots per 16-step chunk
# speedup vs baseline: 1.1533x; 1.0032x over previous
; DI void phase_scan(const Params& P, int l, char* smem) {
;     ...
;       {
;         float4 Ar[4], Aw[4], Ak[4], Aa[4], Ab[4], Br[4], Bw[4], Bk[4], Ba[4], Bb[4];
;         float Av[4], Bv[4];
;         SCAN_LOAD(A, 0);
;         SCAN_LOAD(B, 1);
;         SCAN_STEPS(A, 0);
;         SCAN_LOAD(A, 2);
;         SCAN_STEPS(B, 1);
;         SCAN_LOAD(B, 3);
;         SCAN_STEPS(A, 2);
;         SCAN_STEPS(B, 3);
;       }
.LBB0_513:
	s_add_i32 s8, s20, 1
	s_bitcmp1_b32 s20, 0
	s_cselect_b32 s9, 0x6000, 0
	v_lshl_or_b32 v219, v172, 2, s9
	s_lshl_b32 s10, s19, 2
	s_or_b32 s9, s9, s10
	v_lshl_add_u32 v218, v170, 2, s9
	ds_read_b128 v[40:43], v219 offset:512
	ds_read_b32 v60, v218 offset:1280
	ds_read_b128 v[44:47], v219 offset:768
	ds_read_b128 v[48:51], v219 offset:256
	ds_read_b128 v[52:55], v219 offset:1024
	ds_read_b128 v[56:59], v219
	ds_read_b128 v[64:67], v219 offset:2048
	ds_read_b32 v84, v218 offset:2816
	ds_read_b128 v[68:71], v219 offset:2304
	ds_read_b128 v[72:75], v219 offset:1792
	ds_read_b128 v[76:79], v219 offset:2560
	ds_read_b128 v[80:83], v219 offset:1536
	s_cmp_lt_u32 s20, 16
	s_movk_i32 s9, 0x41ff
	s_cselect_b32 s9, 0xff, s9
	s_andn2_b64 vcc, exec, s[16:17]
	s_waitcnt lgkmcnt(10)
	v_pk_mul_f32 v[156:157], v[60:61], v[40:41] op_sel_hi:[0,1]
	v_pk_mul_f32 v[158:159], v[60:61], v[42:43] op_sel_hi:[0,1]
	s_waitcnt lgkmcnt(4)
	ds_read_b128 v[88:91], v219 offset:3584
	ds_read_b32 v108, v218 offset:4352
	ds_read_b128 v[92:95], v219 offset:3840
	ds_read_b128 v[96:99], v219 offset:3328
	ds_read_b128 v[100:103], v219 offset:4096
	ds_read_b128 v[104:107], v219 offset:3072
	v_pk_mul_f32 v[164:165], v[126:127], v[44:45]
	v_pk_fma_f32 v[164:165], v[128:129], v[46:47], v[164:165]
	v_add_f32_e32 v164, v164, v165
	v_pk_fma_f32 v[156:157], v[126:127], v[48:49], v[156:157]
	v_pk_fma_f32 v[158:159], v[128:129], v[50:51], v[158:159]
	v_add_f32_dpp v164, v164, v164 quad_perm:[1,0,3,2] row_mask:0xf bank_mask:0xf bound_ctrl:1
	s_nop 0
	s_nop 0
	v_add_f32_dpp v164, v164, v164 quad_perm:[2,3,0,1] row_mask:0xf bank_mask:0xf bound_ctrl:1
	s_nop 0
	v_pk_mul_f32 v[160:161], v[84:85], v[64:65] op_sel_hi:[0,1]
	v_add_f32_dpp v164, v164, v164 row_half_mirror row_mask:0xf bank_mask:0xf bound_ctrl:1
	v_pk_mul_f32 v[162:163], v[84:85], v[66:67] op_sel_hi:[0,1]
	s_nop 0
	v_add_f32_dpp v164, v164, v164 row_mirror row_mask:0xf bank_mask:0xf bound_ctrl:1
	v_pk_fma_f32 v[126:127], v[164:165], v[52:53], v[156:157] op_sel_hi:[0,1,1]
	v_pk_fma_f32 v[128:129], v[164:165], v[54:55], v[158:159] op_sel_hi:[0,1,1]
	s_waitcnt lgkmcnt(4)
	ds_read_b128 v[132:135], v219 offset:5120
	ds_read_b32 v152, v218 offset:5888
	ds_read_b128 v[136:139], v219 offset:5376
	ds_read_b128 v[140:143], v219 offset:4864
	ds_read_b128 v[144:147], v219 offset:5632
	ds_read_b128 v[148:151], v219 offset:4608
	v_pk_mul_f32 v[164:165], v[126:127], v[68:69]
	v_pk_fma_f32 v[164:165], v[128:129], v[70:71], v[164:165]
	v_add_f32_e32 v164, v164, v165
	v_pk_fma_f32 v[160:161], v[126:127], v[72:73], v[160:161]
	v_pk_fma_f32 v[162:163], v[128:129], v[74:75], v[162:163]
	v_add_f32_dpp v164, v164, v164 quad_perm:[1,0,3,2] row_mask:0xf bank_mask:0xf bound_ctrl:1
	v_pk_mul_f32 v[166:167], v[126:127], v[56:57]
	v_pk_fma_f32 v[166:167], v[128:129], v[58:59], v[166:167]
	v_add_f32_dpp v164, v164, v164 quad_perm:[2,3,0,1] row_mask:0xf bank_mask:0xf bound_ctrl:1
	v_add_f32_e32 v12, v166, v167
	v_pk_mul_f32 v[156:157], v[108:109], v[88:89] op_sel_hi:[0,1]
	v_add_f32_dpp v164, v164, v164 row_half_mirror row_mask:0xf bank_mask:0xf bound_ctrl:1
	v_pk_mul_f32 v[158:159], v[108:109], v[90:91] op_sel_hi:[0,1]
	s_nop 0
	v_add_f32_dpp v164, v164, v164 row_mirror row_mask:0xf bank_mask:0xf bound_ctrl:1
	v_pk_fma_f32 v[126:127], v[164:165], v[76:77], v[160:161] op_sel_hi:[0,1,1]
	v_pk_fma_f32 v[128:129], v[164:165], v[78:79], v[162:163] op_sel_hi:[0,1,1]
	s_waitcnt lgkmcnt(4)
	ds_read_b128 v[40:43], v219 offset:6656
	ds_read_b32 v60, v218 offset:7424
	ds_read_b128 v[44:47], v219 offset:6912
	ds_read_b128 v[48:51], v219 offset:6400
	ds_read_b128 v[52:55], v219 offset:7168
	ds_read_b128 v[56:59], v219 offset:6144
	v_pk_mul_f32 v[164:165], v[126:127], v[92:93]
	v_pk_fma_f32 v[164:165], v[128:129], v[94:95], v[164:165]
	v_add_f32_e32 v164, v164, v165
	v_pk_fma_f32 v[156:157], v[126:127], v[96:97], v[156:157]
	v_pk_fma_f32 v[158:159], v[128:129], v[98:99], v[158:159]
	v_add_f32_dpp v164, v164, v164 quad_perm:[1,0,3,2] row_mask:0xf bank_mask:0xf bound_ctrl:1
	v_pk_mul_f32 v[166:167], v[126:127], v[80:81]
	v_pk_fma_f32 v[166:167], v[128:129], v[82:83], v[166:167]
	v_add_f32_dpp v164, v164, v164 quad_perm:[2,3,0,1] row_mask:0xf bank_mask:0xf bound_ctrl:1
	v_add_f32_e32 v13, v166, v167
	v_pk_mul_f32 v[160:161], v[152:153], v[132:133] op_sel_hi:[0,1]
	v_add_f32_dpp v164, v164, v164 row_half_mirror row_mask:0xf bank_mask:0xf bound_ctrl:1
	v_pk_mul_f32 v[162:163], v[152:153], v[134:135] op_sel_hi:[0,1]
	s_nop 0
	v_add_f32_dpp v164, v164, v164 row_mirror row_mask:0xf bank_mask:0xf bound_ctrl:1
	v_pk_fma_f32 v[126:127], v[164:165], v[100:101], v[156:157] op_sel_hi:[0,1,1]
	v_pk_fma_f32 v[128:129], v[164:165], v[102:103], v[158:159] op_sel_hi:[0,1,1]
	s_waitcnt lgkmcnt(4)
	ds_read_b128 v[64:67], v219 offset:8192
	ds_read_b32 v84, v218 offset:8960
	ds_read_b128 v[68:71], v219 offset:8448
	ds_read_b128 v[72:75], v219 offset:7936
	ds_read_b128 v[76:79], v219 offset:8704
	ds_read_b128 v[80:83], v219 offset:7680
	v_pk_mul_f32 v[164:165], v[126:127], v[136:137]
	v_pk_fma_f32 v[164:165], v[128:129], v[138:139], v[164:165]
	v_add_f32_e32 v164, v164, v165
	v_pk_fma_f32 v[160:161], v[126:127], v[140:141], v[160:161]
	v_pk_fma_f32 v[162:163], v[128:129], v[142:143], v[162:163]
	v_add_f32_dpp v164, v164, v164 quad_perm:[1,0,3,2] row_mask:0xf bank_mask:0xf bound_ctrl:1
	v_pk_mul_f32 v[166:167], v[126:127], v[104:105]
	v_pk_fma_f32 v[166:167], v[128:129], v[106:107], v[166:167]
	v_add_f32_dpp v164, v164, v164 quad_perm:[2,3,0,1] row_mask:0xf bank_mask:0xf bound_ctrl:1
	v_add_f32_e32 v14, v166, v167
	v_pk_mul_f32 v[156:157], v[60:61], v[40:41] op_sel_hi:[0,1]
	v_add_f32_dpp v164, v164, v164 row_half_mirror row_mask:0xf bank_mask:0xf bound_ctrl:1
	v_pk_mul_f32 v[158:159], v[60:61], v[42:43] op_sel_hi:[0,1]
	s_nop 0
	v_add_f32_dpp v164, v164, v164 row_mirror row_mask:0xf bank_mask:0xf bound_ctrl:1
	v_pk_fma_f32 v[126:127], v[164:165], v[144:145], v[160:161] op_sel_hi:[0,1,1]
	v_pk_fma_f32 v[128:129], v[164:165], v[146:147], v[162:163] op_sel_hi:[0,1,1]
	s_waitcnt lgkmcnt(4)
; DI void phase_scan(const Params& P, int l, char* smem) {
;     ...
;       {
;         float4 Ar[4], Aw[4], Ak[4], Aa[4], Ab[4], Br[4], Bw[4], Bk[4], Ba[4], Bb[4];
;         float Av[4], Bv[4];
;         SCAN_LOAD(A, 0);
;         SCAN_LOAD(B, 1);
;         SCAN_STEPS(A, 0);
;         SCAN_LOAD(A, 2);
;         SCAN_STEPS(B, 1);
;         SCAN_LOAD(B, 3);
;         SCAN_STEPS(A, 2);
;         SCAN_STEPS(B, 3);
;       }
	ds_read_b128 v[88:91], v219 offset:9728
	ds_read_b32 v108, v218 offset:10496
	ds_read_b128 v[92:95], v219 offset:9984
	ds_read_b128 v[96:99], v219 offset:9472
	ds_read_b128 v[100:103], v219 offset:10240
	ds_read_b128 v[104:107], v219 offset:9216
	v_pk_mul_f32 v[164:165], v[126:127], v[44:45]
	v_pk_fma_f32 v[164:165], v[128:129], v[46:47], v[164:165]
	v_add_f32_e32 v164, v164, v165
	v_pk_fma_f32 v[156:157], v[126:127], v[48:49], v[156:157]
	v_pk_fma_f32 v[158:159], v[128:129], v[50:51], v[158:159]
	v_add_f32_dpp v164, v164, v164 quad_perm:[1,0,3,2] row_mask:0xf bank_mask:0xf bound_ctrl:1
	v_pk_mul_f32 v[166:167], v[126:127], v[148:149]
	v_pk_fma_f32 v[166:167], v[128:129], v[150:151], v[166:167]
	v_add_f32_dpp v164, v164, v164 quad_perm:[2,3,0,1] row_mask:0xf bank_mask:0xf bound_ctrl:1
	v_add_f32_e32 v15, v166, v167
	v_pk_mul_f32 v[160:161], v[84:85], v[64:65] op_sel_hi:[0,1]
	v_add_f32_dpp v164, v164, v164 row_half_mirror row_mask:0xf bank_mask:0xf bound_ctrl:1
	v_pk_mul_f32 v[162:163], v[84:85], v[66:67] op_sel_hi:[0,1]
	s_nop 0
	v_add_f32_dpp v164, v164, v164 row_mirror row_mask:0xf bank_mask:0xf bound_ctrl:1
	v_pk_fma_f32 v[126:127], v[164:165], v[52:53], v[156:157] op_sel_hi:[0,1,1]
	v_pk_fma_f32 v[128:129], v[164:165], v[54:55], v[158:159] op_sel_hi:[0,1,1]
	s_waitcnt lgkmcnt(4)
	ds_read_b128 v[132:135], v219 offset:11264
	ds_read_b32 v152, v218 offset:12032
	ds_read_b128 v[136:139], v219 offset:11520
	ds_read_b128 v[140:143], v219 offset:11008
	ds_read_b128 v[144:147], v219 offset:11776
	ds_read_b128 v[148:151], v219 offset:10752
	v_pk_mul_f32 v[164:165], v[126:127], v[68:69]
	v_pk_fma_f32 v[164:165], v[128:129], v[70:71], v[164:165]
	v_add_f32_e32 v164, v164, v165
	v_pk_fma_f32 v[160:161], v[126:127], v[72:73], v[160:161]
	v_pk_fma_f32 v[162:163], v[128:129], v[74:75], v[162:163]
	v_add_f32_dpp v164, v164, v164 quad_perm:[1,0,3,2] row_mask:0xf bank_mask:0xf bound_ctrl:1
	v_pk_mul_f32 v[166:167], v[126:127], v[56:57]
	v_pk_fma_f32 v[166:167], v[128:129], v[58:59], v[166:167]
	v_add_f32_dpp v164, v164, v164 quad_perm:[2,3,0,1] row_mask:0xf bank_mask:0xf bound_ctrl:1
	v_add_f32_e32 v16, v166, v167
	v_pk_mul_f32 v[156:157], v[108:109], v[88:89] op_sel_hi:[0,1]
	v_add_f32_dpp v164, v164, v164 row_half_mirror row_mask:0xf bank_mask:0xf bound_ctrl:1
	v_pk_mul_f32 v[158:159], v[108:109], v[90:91] op_sel_hi:[0,1]
	s_nop 0
	v_add_f32_dpp v164, v164, v164 row_mirror row_mask:0xf bank_mask:0xf bound_ctrl:1
	v_pk_fma_f32 v[126:127], v[164:165], v[76:77], v[160:161] op_sel_hi:[0,1,1]
	v_pk_fma_f32 v[128:129], v[164:165], v[78:79], v[162:163] op_sel_hi:[0,1,1]
	s_waitcnt lgkmcnt(4)
	ds_read_b128 v[40:43], v219 offset:12800
	ds_read_b32 v60, v218 offset:13568
	ds_read_b128 v[44:47], v219 offset:13056
	ds_read_b128 v[48:51], v219 offset:12544
	ds_read_b128 v[52:55], v219 offset:13312
	ds_read_b128 v[56:59], v219 offset:12288
	v_pk_mul_f32 v[164:165], v[126:127], v[92:93]
	v_pk_fma_f32 v[164:165], v[128:129], v[94:95], v[164:165]
	v_add_f32_e32 v164, v164, v165
	v_pk_fma_f32 v[156:157], v[126:127], v[96:97], v[156:157]
	v_pk_fma_f32 v[158:159], v[128:129], v[98:99], v[158:159]
	v_add_f32_dpp v164, v164, v164 quad_perm:[1,0,3,2] row_mask:0xf bank_mask:0xf bound_ctrl:1
	v_pk_mul_f32 v[166:167], v[126:127], v[80:81]
	v_pk_fma_f32 v[166:167], v[128:129], v[82:83], v[166:167]
	v_add_f32_dpp v164, v164, v164 quad_perm:[2,3,0,1] row_mask:0xf bank_mask:0xf bound_ctrl:1
	v_add_f32_e32 v17, v166, v167
	v_pk_mul_f32 v[160:161], v[152:153], v[132:133] op_sel_hi:[0,1]
	v_add_f32_dpp v164, v164, v164 row_half_mirror row_mask:0xf bank_mask:0xf bound_ctrl:1
	v_pk_mul_f32 v[162:163], v[152:153], v[134:135] op_sel_hi:[0,1]
	s_nop 0
	v_add_f32_dpp v164, v164, v164 row_mirror row_mask:0xf bank_mask:0xf bound_ctrl:1
	v_pk_fma_f32 v[126:127], v[164:165], v[100:101], v[156:157] op_sel_hi:[0,1,1]
	v_pk_fma_f32 v[128:129], v[164:165], v[102:103], v[158:159] op_sel_hi:[0,1,1]
	s_waitcnt lgkmcnt(4)
	ds_read_b128 v[64:67], v219 offset:14336
	ds_read_b32 v84, v218 offset:15104
	ds_read_b128 v[68:71], v219 offset:14592
	ds_read_b128 v[72:75], v219 offset:14080
	ds_read_b128 v[76:79], v219 offset:14848
	ds_read_b128 v[80:83], v219 offset:13824
	v_pk_mul_f32 v[164:165], v[126:127], v[136:137]
	v_pk_fma_f32 v[164:165], v[128:129], v[138:139], v[164:165]
	v_add_f32_e32 v164, v164, v165
	v_pk_fma_f32 v[160:161], v[126:127], v[140:141], v[160:161]
	v_pk_fma_f32 v[162:163], v[128:129], v[142:143], v[162:163]
	v_add_f32_dpp v164, v164, v164 quad_perm:[1,0,3,2] row_mask:0xf bank_mask:0xf bound_ctrl:1
	v_pk_mul_f32 v[166:167], v[126:127], v[104:105]
	v_pk_fma_f32 v[166:167], v[128:129], v[106:107], v[166:167]
	v_add_f32_dpp v164, v164, v164 quad_perm:[2,3,0,1] row_mask:0xf bank_mask:0xf bound_ctrl:1
	v_add_f32_e32 v18, v166, v167
	v_pk_mul_f32 v[156:157], v[60:61], v[40:41] op_sel_hi:[0,1]
	v_add_f32_dpp v164, v164, v164 row_half_mirror row_mask:0xf bank_mask:0xf bound_ctrl:1
	v_pk_mul_f32 v[158:159], v[60:61], v[42:43] op_sel_hi:[0,1]
	s_nop 0
	v_add_f32_dpp v164, v164, v164 row_mirror row_mask:0xf bank_mask:0xf bound_ctrl:1
	v_pk_fma_f32 v[126:127], v[164:165], v[144:145], v[160:161] op_sel_hi:[0,1,1]
	v_pk_fma_f32 v[128:129], v[164:165], v[146:147], v[162:163] op_sel_hi:[0,1,1]
	s_waitcnt lgkmcnt(4)
	ds_read_b128 v[88:91], v219 offset:15872
	ds_read_b32 v108, v218 offset:16640
	ds_read_b128 v[92:95], v219 offset:16128
	ds_read_b128 v[96:99], v219 offset:15616
	ds_read_b128 v[100:103], v219 offset:16384
	ds_read_b128 v[104:107], v219 offset:15360
	v_pk_mul_f32 v[164:165], v[126:127], v[44:45]
	v_pk_fma_f32 v[164:165], v[128:129], v[46:47], v[164:165]
	v_add_f32_e32 v164, v164, v165
	v_pk_fma_f32 v[156:157], v[126:127], v[48:49], v[156:157]
	v_pk_fma_f32 v[158:159], v[128:129], v[50:51], v[158:159]
	v_add_f32_dpp v164, v164, v164 quad_perm:[1,0,3,2] row_mask:0xf bank_mask:0xf bound_ctrl:1
	v_pk_mul_f32 v[166:167], v[126:127], v[148:149]
	v_pk_fma_f32 v[166:167], v[128:129], v[150:151], v[166:167]
	v_add_f32_dpp v164, v164, v164 quad_perm:[2,3,0,1] row_mask:0xf bank_mask:0xf bound_ctrl:1
	v_add_f32_e32 v19, v166, v167
	v_pk_mul_f32 v[160:161], v[84:85], v[64:65] op_sel_hi:[0,1]
	v_add_f32_dpp v164, v164, v164 row_half_mirror row_mask:0xf bank_mask:0xf bound_ctrl:1
	v_pk_mul_f32 v[162:163], v[84:85], v[66:67] op_sel_hi:[0,1]
	s_nop 0
	v_add_f32_dpp v164, v164, v164 row_mirror row_mask:0xf bank_mask:0xf bound_ctrl:1
	v_pk_fma_f32 v[126:127], v[164:165], v[52:53], v[156:157] op_sel_hi:[0,1,1]
	v_pk_fma_f32 v[128:129], v[164:165], v[54:55], v[158:159] op_sel_hi:[0,1,1]
	s_waitcnt lgkmcnt(4)
	ds_read_b128 v[132:135], v219 offset:17408
	ds_read_b32 v152, v218 offset:18176
	ds_read_b128 v[136:139], v219 offset:17664
	ds_read_b128 v[140:143], v219 offset:17152
	ds_read_b128 v[144:147], v219 offset:17920
	ds_read_b128 v[148:151], v219 offset:16896
	v_pk_mul_f32 v[164:165], v[126:127], v[68:69]
	v_pk_fma_f32 v[164:165], v[128:129], v[70:71], v[164:165]
	v_add_f32_e32 v164, v164, v165
	v_pk_fma_f32 v[160:161], v[126:127], v[72:73], v[160:161]
	v_pk_fma_f32 v[162:163], v[128:129], v[74:75], v[162:163]
	v_add_f32_dpp v164, v164, v164 quad_perm:[1,0,3,2] row_mask:0xf bank_mask:0xf bound_ctrl:1
	v_pk_mul_f32 v[166:167], v[126:127], v[56:57]
	v_pk_fma_f32 v[166:167], v[128:129], v[58:59], v[166:167]
	v_add_f32_dpp v164, v164, v164 quad_perm:[2,3,0,1] row_mask:0xf bank_mask:0xf bound_ctrl:1
	v_add_f32_e32 v20, v166, v167
	v_pk_mul_f32 v[156:157], v[108:109], v[88:89] op_sel_hi:[0,1]
	v_add_f32_dpp v164, v164, v164 row_half_mirror row_mask:0xf bank_mask:0xf bound_ctrl:1
	v_pk_mul_f32 v[158:159], v[108:109], v[90:91] op_sel_hi:[0,1]
	s_nop 0
	v_add_f32_dpp v164, v164, v164 row_mirror row_mask:0xf bank_mask:0xf bound_ctrl:1
	v_pk_fma_f32 v[126:127], v[164:165], v[76:77], v[160:161] op_sel_hi:[0,1,1]
	v_pk_fma_f32 v[128:129], v[164:165], v[78:79], v[162:163] op_sel_hi:[0,1,1]
	s_waitcnt lgkmcnt(4)
	ds_read_b128 v[40:43], v219 offset:18944
	ds_read_b32 v60, v218 offset:19712
	ds_read_b128 v[44:47], v219 offset:19200
	ds_read_b128 v[48:51], v219 offset:18688
	ds_read_b128 v[52:55], v219 offset:19456
	ds_read_b128 v[56:59], v219 offset:18432
	v_pk_mul_f32 v[164:165], v[126:127], v[92:93]
	v_pk_fma_f32 v[164:165], v[128:129], v[94:95], v[164:165]
	v_add_f32_e32 v164, v164, v165
	v_pk_fma_f32 v[156:157], v[126:127], v[96:97], v[156:157]
	v_pk_fma_f32 v[158:159], v[128:129], v[98:99], v[158:159]
	v_add_f32_dpp v164, v164, v164 quad_perm:[1,0,3,2] row_mask:0xf bank_mask:0xf bound_ctrl:1
	v_pk_mul_f32 v[166:167], v[126:127], v[80:81]
	v_pk_fma_f32 v[166:167], v[128:129], v[82:83], v[166:167]
	v_add_f32_dpp v164, v164, v164 quad_perm:[2,3,0,1] row_mask:0xf bank_mask:0xf bound_ctrl:1
	v_add_f32_e32 v21, v166, v167
	v_pk_mul_f32 v[160:161], v[152:153], v[132:133] op_sel_hi:[0,1]
	v_add_f32_dpp v164, v164, v164 row_half_mirror row_mask:0xf bank_mask:0xf bound_ctrl:1
	v_pk_mul_f32 v[162:163], v[152:153], v[134:135] op_sel_hi:[0,1]
	s_nop 0
	v_add_f32_dpp v164, v164, v164 row_mirror row_mask:0xf bank_mask:0xf bound_ctrl:1
	v_pk_fma_f32 v[126:127], v[164:165], v[100:101], v[156:157] op_sel_hi:[0,1,1]
	v_pk_fma_f32 v[128:129], v[164:165], v[102:103], v[158:159] op_sel_hi:[0,1,1]
	s_waitcnt lgkmcnt(4)
	ds_read_b128 v[64:67], v219 offset:20480
	ds_read_b32 v84, v218 offset:21248
	ds_read_b128 v[68:71], v219 offset:20736
	ds_read_b128 v[72:75], v219 offset:20224
	ds_read_b128 v[76:79], v219 offset:20992
	ds_read_b128 v[80:83], v219 offset:19968
	v_pk_mul_f32 v[164:165], v[126:127], v[136:137]
	v_pk_fma_f32 v[164:165], v[128:129], v[138:139], v[164:165]
	v_add_f32_e32 v164, v164, v165
	v_pk_fma_f32 v[160:161], v[126:127], v[140:141], v[160:161]
	v_pk_fma_f32 v[162:163], v[128:129], v[142:143], v[162:163]
	v_add_f32_dpp v164, v164, v164 quad_perm:[1,0,3,2] row_mask:0xf bank_mask:0xf bound_ctrl:1
	v_pk_mul_f32 v[166:167], v[126:127], v[104:105]
	v_pk_fma_f32 v[166:167], v[128:129], v[106:107], v[166:167]
	v_add_f32_dpp v164, v164, v164 quad_perm:[2,3,0,1] row_mask:0xf bank_mask:0xf bound_ctrl:1
	v_add_f32_e32 v22, v166, v167
	v_pk_mul_f32 v[156:157], v[60:61], v[40:41] op_sel_hi:[0,1]
	v_add_f32_dpp v164, v164, v164 row_half_mirror row_mask:0xf bank_mask:0xf bound_ctrl:1
	v_pk_mul_f32 v[158:159], v[60:61], v[42:43] op_sel_hi:[0,1]
	s_nop 0
	v_add_f32_dpp v164, v164, v164 row_mirror row_mask:0xf bank_mask:0xf bound_ctrl:1
	v_pk_fma_f32 v[126:127], v[164:165], v[144:145], v[160:161] op_sel_hi:[0,1,1]
	v_pk_fma_f32 v[128:129], v[164:165], v[146:147], v[162:163] op_sel_hi:[0,1,1]
	s_waitcnt lgkmcnt(4)
	ds_read_b128 v[88:91], v219 offset:22016
	ds_read_b32 v108, v218 offset:22784
	ds_read_b128 v[92:95], v219 offset:22272
	ds_read_b128 v[96:99], v219 offset:21760
	ds_read_b128 v[100:103], v219 offset:22528
	ds_read_b128 v[104:107], v219 offset:21504
	v_pk_mul_f32 v[164:165], v[126:127], v[44:45]
	v_pk_fma_f32 v[164:165], v[128:129], v[46:47], v[164:165]
	v_add_f32_e32 v164, v164, v165
	v_pk_fma_f32 v[156:157], v[126:127], v[48:49], v[156:157]
	v_pk_fma_f32 v[158:159], v[128:129], v[50:51], v[158:159]
	v_add_f32_dpp v164, v164, v164 quad_perm:[1,0,3,2] row_mask:0xf bank_mask:0xf bound_ctrl:1
	v_pk_mul_f32 v[166:167], v[126:127], v[148:149]
	v_pk_fma_f32 v[166:167], v[128:129], v[150:151], v[166:167]
	v_add_f32_dpp v164, v164, v164 quad_perm:[2,3,0,1] row_mask:0xf bank_mask:0xf bound_ctrl:1
	v_add_f32_e32 v23, v166, v167
	v_pk_mul_f32 v[160:161], v[84:85], v[64:65] op_sel_hi:[0,1]
	v_add_f32_dpp v164, v164, v164 row_half_mirror row_mask:0xf bank_mask:0xf bound_ctrl:1
	v_pk_mul_f32 v[162:163], v[84:85], v[66:67] op_sel_hi:[0,1]
	s_nop 0
	v_add_f32_dpp v164, v164, v164 row_mirror row_mask:0xf bank_mask:0xf bound_ctrl:1
	v_pk_fma_f32 v[126:127], v[164:165], v[52:53], v[156:157] op_sel_hi:[0,1,1]
	v_pk_fma_f32 v[128:129], v[164:165], v[54:55], v[158:159] op_sel_hi:[0,1,1]
	s_waitcnt lgkmcnt(4)
	ds_read_b128 v[132:135], v219 offset:23552
	ds_read_b32 v152, v218 offset:24320
	ds_read_b128 v[136:139], v219 offset:23808
	ds_read_b128 v[140:143], v219 offset:23296
	ds_read_b128 v[144:147], v219 offset:24064
	ds_read_b128 v[148:151], v219 offset:23040
	v_pk_mul_f32 v[164:165], v[126:127], v[68:69]
	v_pk_fma_f32 v[164:165], v[128:129], v[70:71], v[164:165]
	v_add_f32_e32 v164, v164, v165
	v_pk_fma_f32 v[160:161], v[126:127], v[72:73], v[160:161]
	v_pk_fma_f32 v[162:163], v[128:129], v[74:75], v[162:163]
	v_add_f32_dpp v164, v164, v164 quad_perm:[1,0,3,2] row_mask:0xf bank_mask:0xf bound_ctrl:1
	v_pk_mul_f32 v[166:167], v[126:127], v[56:57]
	v_pk_fma_f32 v[166:167], v[128:129], v[58:59], v[166:167]
	v_add_f32_dpp v164, v164, v164 quad_perm:[2,3,0,1] row_mask:0xf bank_mask:0xf bound_ctrl:1
	v_add_f32_e32 v24, v166, v167
	v_pk_mul_f32 v[156:157], v[108:109], v[88:89] op_sel_hi:[0,1]
	v_add_f32_dpp v164, v164, v164 row_half_mirror row_mask:0xf bank_mask:0xf bound_ctrl:1
	v_pk_mul_f32 v[158:159], v[108:109], v[90:91] op_sel_hi:[0,1]
	s_nop 0
	v_add_f32_dpp v164, v164, v164 row_mirror row_mask:0xf bank_mask:0xf bound_ctrl:1
	v_pk_fma_f32 v[126:127], v[164:165], v[76:77], v[160:161] op_sel_hi:[0,1,1]
	v_pk_fma_f32 v[128:129], v[164:165], v[78:79], v[162:163] op_sel_hi:[0,1,1]
	s_waitcnt lgkmcnt(4)
	v_pk_mul_f32 v[164:165], v[126:127], v[92:93]
	v_pk_fma_f32 v[164:165], v[128:129], v[94:95], v[164:165]
	v_add_f32_e32 v164, v164, v165
	v_pk_fma_f32 v[156:157], v[126:127], v[96:97], v[156:157]
	v_pk_fma_f32 v[158:159], v[128:129], v[98:99], v[158:159]
	v_add_f32_dpp v164, v164, v164 quad_perm:[1,0,3,2] row_mask:0xf bank_mask:0xf bound_ctrl:1
	v_pk_mul_f32 v[166:167], v[126:127], v[80:81]
	v_pk_fma_f32 v[166:167], v[128:129], v[82:83], v[166:167]
	v_add_f32_dpp v164, v164, v164 quad_perm:[2,3,0,1] row_mask:0xf bank_mask:0xf bound_ctrl:1
	v_add_f32_e32 v25, v166, v167
	v_pk_mul_f32 v[160:161], v[152:153], v[132:133] op_sel_hi:[0,1]
	v_add_f32_dpp v164, v164, v164 row_half_mirror row_mask:0xf bank_mask:0xf bound_ctrl:1
	v_pk_mul_f32 v[162:163], v[152:153], v[134:135] op_sel_hi:[0,1]
	s_nop 0
	v_add_f32_dpp v164, v164, v164 row_mirror row_mask:0xf bank_mask:0xf bound_ctrl:1
	v_pk_fma_f32 v[126:127], v[164:165], v[100:101], v[156:157] op_sel_hi:[0,1,1]
	v_pk_fma_f32 v[128:129], v[164:165], v[102:103], v[158:159] op_sel_hi:[0,1,1]
	s_waitcnt lgkmcnt(0)
; DI unsigned short f2bf(float x) { return (unsigned short)(pack2(x, 0.f) & 0xffffu); }
; DI float bflo(unsigned u) { return __uint_as_float(u << 16); }
; DI float bfhi(unsigned u) { return __uint_as_float(u & 0xffff0000u); }
; DI void vm_wait5x2(u32x2& a, u32x2& b, u32x2& c, u32x2& d, u32x2& e) { cfence(); }
; DI float fma_(float a, float b, float c) { float d; asm("v_fma_f32 %0, %1, %2, %3" : "=v"(d) : "v"(a), "v"(b), "v"(c)); return d; }
; DI void scan_prep(u32x2 (&raw)[5], const float (&kkw)[4], const float (&kaw)[4], float* dst  ) {
;   vm_wait5x2(raw[0], raw[1], raw[2], raw[3], raw[4]);
;   float r[4] = {bflo(raw[0].x), bfhi(raw[0].x), bflo(raw[0].y), bfhi(raw[0].y)};
;   float k[4] = {bflo(raw[1].x), bfhi(raw[1].x), bflo(raw[1].y), bfhi(raw[1].y)};
;   float v[4] = {bflo(raw[2].x), bfhi(raw[2].x), bflo(raw[2].y), bfhi(raw[2].y)};
;   float e[4] = {bflo(raw[3].x), bfhi(raw[3].x), bflo(raw[3].y), bfhi(raw[3].y)};
;   float a[4] = {bflo(raw[4].x), bfhi(raw[4].x), bflo(raw[4].y), bfhi(raw[4].y)};
;   float kr[4], ss = 0.f;
; #pragma unroll
;   for (int i = 0; i < 4; ++i) { kr[i] = mul_(k[i], kkw[i]); ss = (i < 3) ? fma_(kr[i], kr[i], ss) : fma_n_(kr[i], kr[i], ss); }
;   ss = reduce16(ss);
;   const float inv = __builtin_amdgcn_rcpf(fmaxf(__builtin_amdgcn_sqrtf(ss), 1e-12f));
;   float w4[4], kd4[4], a4[4], b4[4];
; #pragma unroll
;   for (int i = 0; i < 4; ++i) {
;     float kn = kr[i] * inv;
;     w4[i] = __builtin_amdgcn_exp2f(mul_(e[i], -LOG2E));
;     kd4[i] = mul_(k[i], fma_(add_(a[i], -1.f), kaw[i], 1.f));
;     a4[i] = -kn;
;     b4[i] = mul_(kn, a[i]);
;   }
;   *(float4*)(dst) = float4{r[0], r[1], r[2], r[3]};
;   *(float4*)(dst + 64) = float4{w4[0], w4[1], w4[2], w4[3]};
;   *(float4*)(dst + 128) = float4{kd4[0], kd4[1], kd4[2], kd4[3]};
;   *(float4*)(dst + 192) = float4{a4[0], a4[1], a4[2], a4[3]};
;   *(float4*)(dst + 256) = float4{b4[0], b4[1], b4[2], b4[3]};
;   *(float4*)(dst + 320) = float4{v[0], v[1], v[2], v[3]};
; }
; DI void phase_scan(const Params& P, int l, char* smem) {
;     ...
;       {
;         int i = c * 16 + kl;
;         int s = dir == 0 ? i : (i < 256 ? 255 - i : 16895 - i);
;         Y[((size_t)b * SB + s) * 1024 + st] = f2bf(ykeep);
;       }
;       if (c + 1 < nchunk) scan_prep(raw, kkw, kaw, buf + ((c + 1) & 1) * (16 * 384) + st * 384 + k4);
	v_pk_mul_f32 v[164:165], v[126:127], v[136:137]
	v_pk_fma_f32 v[164:165], v[128:129], v[138:139], v[164:165]
	v_add_f32_e32 v164, v164, v165
	v_pk_fma_f32 v[160:161], v[126:127], v[140:141], v[160:161]
	v_pk_fma_f32 v[162:163], v[128:129], v[142:143], v[162:163]
	v_add_f32_dpp v164, v164, v164 quad_perm:[1,0,3,2] row_mask:0xf bank_mask:0xf bound_ctrl:1
	v_pk_mul_f32 v[166:167], v[126:127], v[104:105]
	v_pk_fma_f32 v[166:167], v[128:129], v[106:107], v[166:167]
	v_add_f32_dpp v164, v164, v164 quad_perm:[2,3,0,1] row_mask:0xf bank_mask:0xf bound_ctrl:1
	v_add_f32_e32 v26, v166, v167
	s_nop 0
	v_add_f32_dpp v164, v164, v164 row_half_mirror row_mask:0xf bank_mask:0xf bound_ctrl:1
	s_nop 0
	s_nop 0
	v_add_f32_dpp v164, v164, v164 row_mirror row_mask:0xf bank_mask:0xf bound_ctrl:1
	v_pk_fma_f32 v[126:127], v[164:165], v[144:145], v[160:161] op_sel_hi:[0,1,1]
	v_pk_fma_f32 v[128:129], v[164:165], v[146:147], v[162:163] op_sel_hi:[0,1,1]
	v_pk_mul_f32 v[166:167], v[126:127], v[148:149]
	v_pk_fma_f32 v[166:167], v[128:129], v[150:151], v[166:167]
	v_add_f32_e32 v27, v166, v167
	v_add_f32_dpp v12, v12, v12 row_ror:8 row_mask:0xf bank_mask:0x3 bound_ctrl:1
	v_add_f32_dpp v12, v20, v20 row_ror:8 row_mask:0xf bank_mask:0xc bound_ctrl:1
	v_add_f32_dpp v13, v13, v13 row_ror:8 row_mask:0xf bank_mask:0x3 bound_ctrl:1
	v_add_f32_dpp v13, v21, v21 row_ror:8 row_mask:0xf bank_mask:0xc bound_ctrl:1
	v_add_f32_dpp v14, v14, v14 row_ror:8 row_mask:0xf bank_mask:0x3 bound_ctrl:1
	v_add_f32_dpp v14, v22, v22 row_ror:8 row_mask:0xf bank_mask:0xc bound_ctrl:1
	v_add_f32_dpp v15, v15, v15 row_ror:8 row_mask:0xf bank_mask:0x3 bound_ctrl:1
	v_add_f32_dpp v15, v23, v23 row_ror:8 row_mask:0xf bank_mask:0xc bound_ctrl:1
	v_add_f32_dpp v16, v16, v16 row_ror:8 row_mask:0xf bank_mask:0x3 bound_ctrl:1
	v_add_f32_dpp v16, v24, v24 row_ror:8 row_mask:0xf bank_mask:0xc bound_ctrl:1
	v_add_f32_dpp v17, v17, v17 row_ror:8 row_mask:0xf bank_mask:0x3 bound_ctrl:1
	v_add_f32_dpp v17, v25, v25 row_ror:8 row_mask:0xf bank_mask:0xc bound_ctrl:1
	v_add_f32_dpp v18, v18, v18 row_ror:8 row_mask:0xf bank_mask:0x3 bound_ctrl:1
	v_add_f32_dpp v18, v26, v26 row_ror:8 row_mask:0xf bank_mask:0xc bound_ctrl:1
	v_add_f32_dpp v19, v19, v19 row_ror:8 row_mask:0xf bank_mask:0x3 bound_ctrl:1
	v_add_f32_dpp v19, v27, v27 row_ror:8 row_mask:0xf bank_mask:0xc bound_ctrl:1
	v_add_f32_dpp v12, v12, v12 row_half_mirror row_mask:0xf bank_mask:0x5 bound_ctrl:1
	v_add_f32_dpp v12, v16, v16 row_half_mirror row_mask:0xf bank_mask:0xa bound_ctrl:1
	v_add_f32_dpp v13, v13, v13 row_half_mirror row_mask:0xf bank_mask:0x5 bound_ctrl:1
	v_add_f32_dpp v13, v17, v17 row_half_mirror row_mask:0xf bank_mask:0xa bound_ctrl:1
	v_add_f32_dpp v14, v14, v14 row_half_mirror row_mask:0xf bank_mask:0x5 bound_ctrl:1
	v_add_f32_dpp v14, v18, v18 row_half_mirror row_mask:0xf bank_mask:0xa bound_ctrl:1
	v_add_f32_dpp v15, v15, v15 row_half_mirror row_mask:0xf bank_mask:0x5 bound_ctrl:1
	v_add_f32_dpp v15, v19, v19 row_half_mirror row_mask:0xf bank_mask:0xa bound_ctrl:1
	s_mov_b32 s10, 0x33333333
	s_mov_b32 s11, 0x33333333
	v_add_f32_dpp v28, v12, v12 quad_perm:[2,3,0,1] row_mask:0xf bank_mask:0xf bound_ctrl:1
	v_add_f32_dpp v29, v14, v14 quad_perm:[2,3,0,1] row_mask:0xf bank_mask:0xf bound_ctrl:1
	v_add_f32_dpp v30, v13, v13 quad_perm:[2,3,0,1] row_mask:0xf bank_mask:0xf bound_ctrl:1
	v_add_f32_dpp v31, v15, v15 quad_perm:[2,3,0,1] row_mask:0xf bank_mask:0xf bound_ctrl:1
	v_cndmask_b32_e64 v28, v29, v28, s[10:11]
	v_cndmask_b32_e64 v30, v31, v30, s[10:11]
	s_mov_b32 s10, 0x55555555
	s_mov_b32 s11, 0x55555555
	v_add_f32_dpp v29, v28, v28 quad_perm:[1,0,3,2] row_mask:0xf bank_mask:0xf bound_ctrl:1
	v_add_f32_dpp v31, v30, v30 quad_perm:[1,0,3,2] row_mask:0xf bank_mask:0xf bound_ctrl:1
	v_cndmask_b32_e64 v11, v31, v29, s[10:11]
	v_add_u32_e32 v10, s9, v216
	v_cndmask_b32_e64 v10, v10, v217, s[4:5]
	v_cvt_pk_bf16_f32 v12, v11, s0
	v_ashrrev_i32_e32 v11, 31, v10
	v_lshl_add_u64 v[10:11], s[6:7], 0, v[10:11]
	v_lshlrev_b64 v[10:11], 11, v[10:11]
	v_lshl_add_u64 v[10:11], v[188:189], 0, v[10:11]
	global_store_short v[10:11], v12, off
	s_cbranch_vccnz .LBB0_510
	s_waitcnt vmcnt(4)
	v_lshlrev_b32_e32 v11, 16, v176
	v_mul_f32 v12, v11, v2
	v_and_b32_e32 v15, 0xffff0000, v176
	v_fma_f32 v10, v12, v12, v1
	v_mul_f32 v13, v15, v3
	v_lshlrev_b32_e32 v16, 16, v177
	v_fma_f32 v10, v13, v13, v10
	v_mul_f32 v28, v16, v4
	v_and_b32_e32 v17, 0xffff0000, v177
	v_fma_f32 v10, v28, v28, v10
	v_mul_f32 v29, v17, v5
	s_waitcnt vmcnt(2)
	v_lshlrev_b32_e32 v14, 16, v178
	v_fma_f32 v10, v29, v29, v10
	s_nop 1
	s_waitcnt vmcnt(1)
	v_lshlrev_b32_e32 v26, 16, v182
	v_lshlrev_b32_e32 v33, 16, v179
	v_add_f32_dpp v10, v10, v10 quad_perm:[1,0,3,2] row_mask:0xf bank_mask:0xf bound_ctrl:1
	v_and_b32_e32 v27, 0xffff0000, v182
	v_and_b32_e32 v30, 0xffff0000, v178
	v_add_f32_dpp v10, v10, v10 quad_perm:[2,3,0,1] row_mask:0xf bank_mask:0xf bound_ctrl:1
	v_lshlrev_b32_e32 v35, 16, v183
	v_and_b32_e32 v37, 0xffff0000, v179
	v_add_f32_dpp v10, v10, v10 row_half_mirror row_mask:0xf bank_mask:0xf bound_ctrl:1
	s_bitcmp1_b32 s8, 0
	s_cselect_b32 s9, 0x6000, 0
	v_add_f32_dpp v10, v10, v10 row_mirror row_mask:0xf bank_mask:0xf bound_ctrl:1
	v_sqrt_f32_e32 v10, v10
	v_add_u32_e32 v34, s9, v192
	v_and_b32_e32 v36, 0xffff0000, v183
	v_and_b32_e32 v25, 0xffff0000, v175
	v_max_f32_e32 v10, 0x2b8cbccc, v10
	v_rcp_f32_e32 v32, v10
	v_mul_f32 v10, v14, v196
	v_add_f32 v14, v26, v197
	v_lshlrev_b32_e32 v24, 16, v175
	v_fma_f32 v14, v14, v6, v198
	v_pk_mul_f32 v[12:13], v[12:13], v[32:33] op_sel_hi:[1,0]
	v_mul_f32 v14, v11, v14
	v_mul_f32 v11, v30, v196
	v_add_f32 v30, v27, v197
	v_exp_f32_e32 v10, v10
	v_xor_b32_e32 v31, 0x80000000, v13
	v_mul_f32 v27, v13, v27
	v_add_f32 v13, v35, v197
	v_fma_f32 v30, v30, v7, v198
	v_mul_f32 v26, v12, v26
	v_exp_f32_e32 v11, v11
	v_fma_f32 v13, v13, v8, v198
	v_mul_f32 v15, v15, v30
	v_xor_b32_e32 v30, 0x80000000, v12
	v_mul_f32 v12, v33, v196
	v_mul_f32 v16, v16, v13
	v_mul_f32 v13, v37, v196
	v_pk_mul_f32 v[28:29], v[28:29], v[32:33] op_sel_hi:[1,0]
	v_exp_f32_e32 v12, v12
	v_exp_f32_e32 v13, v13
	v_and_b32_e32 v23, 0xffff0000, v174
	v_lshlrev_b32_e32 v22, 16, v174
	v_xor_b32_e32 v32, 0x80000000, v28
	v_mul_f32 v28, v28, v35
	v_add_f32 v35, v36, v197
	v_and_b32_e32 v21, 0xffff0000, v181
	v_lshlrev_b32_e32 v20, 16, v181
	v_and_b32_e32 v19, 0xffff0000, v180
	v_lshlrev_b32_e32 v18, 16, v180
	v_xor_b32_e32 v33, 0x80000000, v29
	v_fma_f32 v35, v35, v9, v198
	v_mul_f32 v29, v29, v36
	s_nop 0
	v_mul_f32 v17, v17, v35
	ds_write_b128 v34, v[22:25]
	ds_write_b128 v34, v[10:13] offset:256
	ds_write_b128 v34, v[14:17] offset:512
	ds_write_b128 v34, v[30:33] offset:768
	ds_write_b128 v34, v[26:29] offset:1024
	ds_write_b128 v34, v[18:21] offset:1280
	s_branch .LBB0_510
